# v75 + attention: waves 4-7 swap query halves so each SIMD pairs one wave of each half (their skipped / partially masked tiles no longer coincide on a SIMD)
# baseline (speedup 1.0000x reference)
.LBB0_300:
	s_cmp_lt_i32 s90, 4
	s_cselect_b64 s[4:5], -1, 0
	s_and_b64 s[0:1], s[4:5], s[2:3]
	s_andn2_b64 vcc, exec, s[0:1]
	s_cbranch_vccnz .LBB0_353
	v_writelane_b32 v254, s4, 32
	v_bfe_u32 v186, v248, 8, 1
	v_lshlrev_b32_e32 v186, 6, v186
	v_xor_b32_e32 v186, v186, v248
	s_nop 0
	v_writelane_b32 v254, s5, 33
	v_and_b32_e32 v187, 63, v186
	v_readlane_b32 s0, v254, 16
	v_lshlrev_b32_e32 v0, 2, v187
	v_readlane_b32 s6, v254, 22
	v_readlane_b32 s7, v254, 23
	v_readlane_b32 s8, v254, 24
	v_readlane_b32 s9, v254, 25
	s_nop 2
	global_load_dword v2, v0, s[6:7]
	s_nop 0
	global_load_dword v3, v0, s[8:9]
	v_mbcnt_lo_u32_b32 v0, -1, 0
	v_mbcnt_hi_u32_b32 v9, -1, v0
	v_and_b32_e32 v0, 64, v9
	v_xor_b32_e32 v1, 1, v9
	v_add_u32_e32 v13, 64, v0
	v_cmp_lt_i32_e32 vcc, v1, v13
	v_xor_b32_e32 v4, 2, v9
	v_xor_b32_e32 v5, 4, v9
	v_cndmask_b32_e32 v0, v9, v1, vcc
	v_cmp_lt_i32_e32 vcc, v4, v13
	v_lshlrev_b32_e32 v1, 2, v0
	v_xor_b32_e32 v10, 8, v9
	v_cndmask_b32_e32 v6, v9, v4, vcc
	v_lshlrev_b32_e32 v0, 2, v6
	v_cmp_lt_i32_e32 vcc, v5, v13
	v_xor_b32_e32 v11, 16, v9
	v_xor_b32_e32 v12, 32, v9
	s_mov_b32 s0, 0x42700000
	v_readlane_b32 s2, v254, 18
	v_readlane_b32 s3, v254, 19
	v_readlane_b32 s1, v254, 17
	v_readlane_b32 s4, v254, 20
	v_readlane_b32 s5, v254, 21
	v_readlane_b32 s10, v254, 26
	v_readlane_b32 s11, v254, 27
	v_readlane_b32 s12, v254, 28
	v_readlane_b32 s13, v254, 29
	v_readlane_b32 s14, v254, 30
	v_readlane_b32 s15, v254, 31
	s_waitcnt vmcnt(0)
	v_and_b32_e32 v8, 0x7fffffff, v2
	v_and_b32_e32 v4, 0x7fffffff, v3
	ds_bpermute_b32 v14, v1, v8
	ds_bpermute_b32 v15, v1, v4
	v_max_f32_e64 v6, |v2|, |v2|
	v_max_f32_e64 v7, |v3|, |v3|
	s_waitcnt lgkmcnt(1)
	v_max_f32_e32 v2, v14, v14
	s_waitcnt lgkmcnt(0)
	v_max_f32_e32 v3, v15, v15
	v_max_f32_e32 v14, v6, v2
	v_max_f32_e32 v3, v7, v3
	ds_bpermute_b32 v15, v0, v14
	ds_bpermute_b32 v16, v0, v3
	v_cndmask_b32_e32 v2, v9, v5, vcc
	v_lshlrev_b32_e32 v2, 2, v2
	v_cmp_lt_i32_e32 vcc, v10, v13
	s_waitcnt lgkmcnt(1)
	v_max_f32_e32 v5, v15, v15
	s_waitcnt lgkmcnt(0)
	v_max_f32_e32 v15, v16, v16
	v_max_f32_e32 v5, v14, v5
	v_max_f32_e32 v14, v3, v15
	ds_bpermute_b32 v15, v2, v5
	ds_bpermute_b32 v16, v2, v14
	v_cndmask_b32_e32 v3, v9, v10, vcc
	v_lshlrev_b32_e32 v3, 2, v3
	v_cmp_lt_i32_e32 vcc, v11, v13
	s_waitcnt lgkmcnt(1)
	v_max_f32_e32 v10, v15, v15
	s_waitcnt lgkmcnt(0)
	v_max_f32_e32 v15, v16, v16
	v_max_f32_e32 v10, v5, v10
	v_max_f32_e32 v14, v14, v15
	ds_bpermute_b32 v15, v3, v10
	ds_bpermute_b32 v16, v3, v14
	v_cndmask_b32_e32 v5, v9, v11, vcc
	v_lshlrev_b32_e32 v5, 2, v5
	v_cmp_lt_i32_e32 vcc, v12, v13
	s_waitcnt lgkmcnt(1)
	v_max_f32_e32 v11, v15, v15
	s_waitcnt lgkmcnt(0)
	v_max_f32_e32 v15, v16, v16
	v_max_f32_e32 v10, v10, v11
	v_max_f32_e32 v11, v14, v15
	ds_bpermute_b32 v14, v5, v10
	ds_bpermute_b32 v15, v5, v11
	v_cndmask_b32_e32 v9, v9, v12, vcc
	v_lshlrev_b32_e32 v192, 2, v9
	s_waitcnt lgkmcnt(1)
	v_max_f32_e32 v9, v14, v14
	s_waitcnt lgkmcnt(0)
	v_max_f32_e32 v12, v15, v15
	v_max_f32_e32 v9, v10, v9
	v_max_f32_e32 v10, v11, v12
	ds_bpermute_b32 v11, v192, v9
	ds_bpermute_b32 v12, v192, v10
	s_waitcnt lgkmcnt(1)
	v_max_f32_e32 v11, v11, v11
	s_waitcnt lgkmcnt(0)
	v_max_f32_e32 v12, v12, v12
	v_max_f32_e32 v9, v9, v11
	v_max_f32_e32 v10, v10, v12
	v_mul_f32_e32 v9, 0x413c5bb7, v9
	v_mul_f32_e32 v9, v10, v9
	v_cmp_gt_f32_e32 vcc, s0, v9
	s_nop 1
	v_cndmask_b32_e64 v9, 0, 1, vcc
	s_nop 0
	v_readfirstlane_b32 s0, v9
	s_and_b32 s0, s0, 1
	s_add_u32 s2, s88, 0x16000000
	s_addc_u32 s3, s89, 0
	s_cmp_eq_u32 s0, 0
	s_mov_b64 s[0:1], -1
	s_cbranch_scc0 .LBB0_327
	ds_bpermute_b32 v8, v1, v8
	ds_bpermute_b32 v1, v1, v4
	v_writelane_b32 v254, s94, 34
	v_writelane_b32 v255, s81, 5
	s_cmpk_gt_i32 s81, 0x8ff
	s_waitcnt lgkmcnt(1)
	v_max_f32_e32 v4, v8, v8
	s_waitcnt lgkmcnt(0)
	v_max_f32_e32 v1, v1, v1
	v_max_f32_e32 v4, v6, v4
	v_max_f32_e32 v1, v7, v1
	ds_bpermute_b32 v6, v0, v4
	ds_bpermute_b32 v0, v0, v1
	v_writelane_b32 v254, s95, 35
	v_writelane_b32 v254, s93, 36
	v_writelane_b32 v254, s92, 37
	s_waitcnt lgkmcnt(1)
	v_max_f32_e32 v6, v6, v6
	s_waitcnt lgkmcnt(0)
	v_max_f32_e32 v0, v0, v0
	v_max_f32_e32 v4, v4, v6
	v_max_f32_e32 v0, v1, v0
	ds_bpermute_b32 v1, v2, v4
	ds_bpermute_b32 v2, v2, v0
	v_writelane_b32 v254, s86, 38
	v_readfirstlane_b32 s0, v186
	s_waitcnt lgkmcnt(1)
	v_max_f32_e32 v1, v1, v1
	s_waitcnt lgkmcnt(0)
	v_max_f32_e32 v2, v2, v2
	v_max_f32_e32 v1, v4, v1
	v_max_f32_e32 v0, v0, v2
	ds_bpermute_b32 v2, v3, v1
	ds_bpermute_b32 v3, v3, v0
	v_writelane_b32 v254, s87, 39
	v_writelane_b32 v254, s88, 49
	s_waitcnt lgkmcnt(1)
	v_max_f32_e32 v2, v2, v2
	s_waitcnt lgkmcnt(0)
	v_max_f32_e32 v3, v3, v3
	v_max_f32_e32 v1, v1, v2
	v_max_f32_e32 v0, v0, v3
	ds_bpermute_b32 v2, v5, v1
	ds_bpermute_b32 v3, v5, v0
	v_writelane_b32 v254, s89, 50
	v_writelane_b32 v254, s90, 51
	v_writelane_b32 v254, s91, 52
	s_waitcnt lgkmcnt(1)
	v_max_f32_e32 v2, v2, v2
	s_waitcnt lgkmcnt(0)
	v_max_f32_e32 v3, v3, v3
	v_max_f32_e32 v1, v1, v2
	v_max_f32_e32 v0, v0, v3
	ds_bpermute_b32 v3, v192, v1
	ds_bpermute_b32 v2, v192, v0
	v_writelane_b32 v254, s84, 40
	s_nop 1
	v_writelane_b32 v254, s85, 41
	s_cbranch_scc1 .LBB0_326
	v_readlane_b32 s4, v254, 40
	v_readlane_b32 s5, v254, 41
	s_cmpk_eq_i32 s4, 0x100
	s_cselect_b64 s[4:5], -1, 0
	s_ashr_i32 s1, s0, 7
	v_writelane_b32 v254, s4, 42
	s_and_b32 s8, s0, 64
	s_lshl_b32 s0, s1, 6
	v_writelane_b32 v254, s5, 43
	s_and_b32 s0, s0, 0xc0
	v_writelane_b32 v254, s1, 44
	s_add_u32 s0, s2, s0
	s_waitcnt lgkmcnt(1)
	v_max_f32_e32 v3, v3, v3
	v_max_f32_e32 v1, v1, v1
	v_writelane_b32 v254, s0, 45
	s_addc_u32 s0, s3, 0
	v_max_f32_e32 v1, v1, v3
	s_waitcnt lgkmcnt(0)
	v_max_f32_e32 v2, v2, v2
	v_max_f32_e32 v0, v0, v0
	v_writelane_b32 v254, s0, 46
	v_cmp_gt_u32_e64 s[0:1], 32, v187
	v_max_f32_e32 v0, v0, v2
	v_mul_f32_e32 v1, 0x413c5bb7, v1
	v_writelane_b32 v254, s0, 47
	v_mul_f32_e32 v188, v0, v1
	v_and_b32_e32 v1, 7, v186
	v_ashrrev_i32_e32 v170, 3, v186
	v_writelane_b32 v254, s1, 48
	s_movk_i32 s0, 0x90
	v_lshrrev_b32_e32 v6, 5, v187
	v_lshlrev_b32_e32 v4, 3, v1
	v_lshlrev_b32_e32 v1, 4, v1
	v_mul_lo_u32 v7, v170, s0
	v_readlane_b32 s4, v254, 49
	v_and_b32_e32 v168, 31, v186
	v_lshrrev_b32_e32 v3, 2, v186
	v_mov_b32_e32 v173, 0
	v_lshlrev_b32_e32 v172, 3, v6
	v_add3_u32 v189, 0, v1, v7
	v_lshl_add_u32 v1, v6, 4, 0
	v_lshlrev_b32_e32 v6, 2, v6
	v_readlane_b32 s5, v254, 50
	v_sub_u32_e32 v8, v168, v6
	v_and_or_b32 v3, v3, 3, v6
	v_lshl_add_u64 v[6:7], s[4:5], 0, v[172:173]
	s_mov_b64 s[0:1], 0xd000000
	v_lshl_add_u64 v[174:175], v[6:7], 0, s[0:1]
	v_cmp_lt_i32_e64 s[0:1], -1, v8
	v_readlane_b32 s6, v254, 51
	v_readlane_b32 s7, v254, 52
	v_writelane_b32 v254, s0, 53
	v_and_b32_e32 v5, 16, v186
	v_lshlrev_b32_e32 v2, 3, v186
	v_writelane_b32 v254, s1, 54
	v_cmp_gt_i32_e64 s[0:1], 1, v8
	v_lshlrev_b32_e32 v0, 5, v186
	v_and_b32_e32 v2, 24, v2
	v_writelane_b32 v254, s0, 55
	v_lshlrev_b32_e32 v5, 1, v5
	v_and_b32_e32 v0, 0x80, v0
	v_writelane_b32 v254, s1, 56
	v_cmp_lt_i32_e64 s[0:1], 0, v8
	v_add3_u32 v5, 0, v5, v2
	v_mul_u32_u24_e32 v6, 0x90, v168
	v_writelane_b32 v254, s0, 57
	v_mul_u32_u24_e32 v3, 0x90, v3
	s_mov_b32 s9, 0
	v_writelane_b32 v254, s1, 58
	v_cmp_gt_i32_e64 s[0:1], 2, v8
	v_mov_b32_e32 v169, v173
	v_ashrrev_i32_e32 v171, 31, v170
	v_writelane_b32 v254, s0, 59
	v_cmp_gt_i32_e64 s[18:19], 4, v8
	v_cmp_lt_i32_e64 s[24:25], 7, v8
	v_writelane_b32 v254, s1, 60
	v_cmp_lt_i32_e64 s[0:1], 1, v8
	v_cmp_gt_i32_e64 s[94:95], 9, v8
	v_cmp_lt_i32_e64 s[96:97], 8, v8
	v_writelane_b32 v254, s0, 61
	v_cmp_gt_i32_e64 s[92:93], 10, v8
	v_cmp_lt_i32_e64 s[28:29], 9, v8
	v_writelane_b32 v254, s1, 62
	v_cmp_gt_i32_e64 s[0:1], 3, v8
	v_cmp_gt_i32_e64 s[30:31], 11, v8
	v_cmp_lt_i32_e64 s[34:35], 10, v8
	v_writelane_b32 v254, s0, 63
	v_cmp_gt_i32_e64 s[36:37], 12, v8
	v_cmp_lt_i32_e64 s[38:39], 15, v8
	v_writelane_b32 v255, s1, 0
	v_cmp_lt_i32_e64 s[0:1], 2, v8
	v_cmp_gt_i32_e64 s[40:41], 17, v8
	v_cmp_lt_i32_e64 s[42:43], 16, v8
	v_writelane_b32 v255, s0, 1
	v_cmp_gt_i32_e64 s[44:45], 18, v8
	v_cmp_lt_i32_e64 s[46:47], 17, v8
	v_writelane_b32 v255, s1, 2
	v_writelane_b32 v255, s8, 3
	s_sub_i32 s0, 0xfffffe80, s8
	v_writelane_b32 v255, s0, 4
	v_cmp_gt_i32_e64 s[48:49], 19, v8
	v_cmp_lt_i32_e64 s[50:51], 18, v8
	v_cmp_gt_i32_e64 s[52:53], 20, v8
	v_cmp_lt_i32_e64 s[54:55], 23, v8
	v_cmp_gt_i32_e64 s[56:57], 25, v8
	v_cmp_lt_i32_e64 s[58:59], 24, v8
	v_cmp_gt_i32_e64 s[60:61], 26, v8
	v_cmp_lt_i32_e64 s[62:63], 25, v8
	v_cmp_gt_i32_e64 s[64:65], 27, v8
	v_cmp_lt_i32_e64 s[66:67], 26, v8
	v_cmp_gt_i32_e64 s[68:69], 28, v8
	s_movk_i32 s33, 0xc00
	v_lshlrev_b32_e32 v176, 1, v172
	v_lshlrev_b32_e32 v178, 1, v4
	v_lshlrev_b32_e32 v172, 1, v0
	v_lshlrev_b32_e32 v180, 1, v2
	v_add_u32_e32 v190, v1, v6
	v_add_u32_e32 v191, v5, v3
	v_mov_b32_e32 v177, v173
	v_mov_b32_e32 v193, 0xf149f2ca
	v_readlane_b32 s10, v255, 5
	s_branch .LBB0_305
